# expert token tail: residual row X loaded and stored with nt (keeps the gathered tables in cache)
# speedup vs baseline: 1.0139x; 1.0043x over previous
; __device__ __forceinline__ float rl_f(float v, int l) { return __uint_as_float(__builtin_amdgcn_readlane(__float_as_uint(v), l)); }
; __device__ __forceinline__ void wr_lane(float& dst, float val_uniform, int lane_uniform, int lane) { asm volatile("" : "+s"(lane_uniform)); dst = (lane == lane_uniform) ? val_uniform : dst; }
; __device__ __forceinline__ void fma_row6(float (&out)[32], const Row6& R, float w) {
;     const v32f f = dq_row6(R, out[0]);
; #pragma unroll
;     for (int i = 0; i < 32; ++i) out[i] = fmaf(w, f[i], out[i]);
; __device__ __forceinline__ void peer_expert_tokens(const Ctx& F, CParams& P, int layer, int m_rows_all, bool last, bool dry, bool hide, unsigned* selflag, int k_lo, int k_hi) {
;     ...
;             for (int k = 0; k < 64; k += 8) {
; #pragma unroll
;                 for (int q = 0; q < 4; ++q) ld_row6(B[q], tabc, __builtin_amdgcn_readlane(idc, k + 4 + q), lane);
;                 if (seg < 2) { const float d0 = dot_row6(A[0], hf, chain), d1 = dot_row6(A[1], hf, chain), d2 = dot_row6(A[2], hf, chain), d3 = dot_row6(A[3], hf, chain); const float b = reduce4(d0, d1, d2, d3, lane);
; #pragma unroll
;                     for (int q = 0; q < 4; ++q) wr_lane(acc, rl_f(b, 16 * q), k + q, lane); }
;                 else {
; #pragma unroll
;                     for (int q = 0; q < 4; ++q) fma_row6(out, A[q], rl_f(wr, k + q)); }
;                 { const bool nx = k + 8 >= 64;
; #pragma unroll
;                   for (int q = 0; q < 4; ++q) { const int ec = __builtin_amdgcn_readlane(idc, (k + 8 + q) & 63), en = __builtin_amdgcn_readlane(idn, q);
;                       ld_row6(A[q], nx ? tabn : tabc, nx ? en : ec, lane); } }
;                 if (seg < 2) { const float d0 = dot_row6(B[0], hf, chain), d1 = dot_row6(B[1], hf, chain), d2 = dot_row6(B[2], hf, chain), d3 = dot_row6(B[3], hf, chain); const float b = reduce4(d0, d1, d2, d3, lane);
; #pragma unroll
;                     for (int q = 0; q < 4; ++q) wr_lane(acc, rl_f(b, 16 * q), k + 4 + q, lane); }
;                 else {
; #pragma unroll
;                     for (int q = 0; q < 4; ++q) fma_row6(out, B[q], rl_f(wr, k + 4 + q)); }
.LBB0_2897:
	s_add_i32 s14, s91, 12
	v_readlane_b32 s18, v140, s14
	s_add_i32 s15, s91, 8
	v_readlane_b32 s56, v179, s14
	s_mul_hi_i32 s14, s18, 0x600
	s_mulk_i32 s18, 0x600
	s_add_u32 s28, s75, s18
	s_addc_u32 s29, s52, s14
	s_add_i32 s14, s91, 13
	v_readlane_b32 s18, v140, s14
	v_readlane_b32 s66, v179, s14
	s_mul_hi_i32 s14, s18, 0x600
	s_mulk_i32 s18, 0x600
	v_lshl_add_u64 v[0:1], s[28:29], 0, v[84:85]
	v_lshl_add_u64 v[2:3], s[28:29], 0, v[86:87]
	s_add_u32 s28, s75, s18
	s_addc_u32 s29, s52, s14
	s_add_i32 s14, s91, 14
	v_readlane_b32 s18, v140, s14
	v_readlane_b32 s80, v179, s14
	s_mul_hi_i32 s14, s18, 0x600
	s_mulk_i32 s18, 0x600
	global_load_dwordx4 v[58:61], v[0:1], off
	global_load_dwordx2 v[62:63], v[2:3], off offset:1024
	v_lshl_add_u64 v[0:1], s[28:29], 0, v[84:85]
	v_lshl_add_u64 v[2:3], s[28:29], 0, v[86:87]
	s_add_u32 s28, s75, s18
	s_addc_u32 s29, s52, s14
	s_add_i32 s14, s91, 15
	v_readlane_b32 s18, v140, s14
	v_readlane_b32 s94, v179, s14
	s_mul_hi_i32 s14, s18, 0x600
	s_mulk_i32 s18, 0x600
	global_load_dwordx4 v[64:67], v[0:1], off
	global_load_dwordx2 v[68:69], v[2:3], off offset:1024
	v_lshl_add_u64 v[0:1], s[28:29], 0, v[84:85]
	v_lshl_add_u64 v[2:3], s[28:29], 0, v[86:87]
	s_add_u32 s28, s75, s18
	s_addc_u32 s29, s52, s14
	s_add_i32 s14, s91, 11
	s_add_i32 s18, s91, 10
	s_add_i32 s46, s91, 9
	s_add_i32 s62, s91, 16
	s_cmp_gt_u32 s15, 55
	s_cselect_b64 vcc, -1, 0
	global_load_dwordx4 v[76:79], v[0:1], off
	global_load_dwordx2 v[80:81], v[2:3], off offset:1024
	v_lshl_add_u64 v[0:1], s[28:29], 0, v[84:85]
	v_lshl_add_u64 v[2:3], s[28:29], 0, v[86:87]
	s_and_b64 s[28:29], vcc, exec
	v_readlane_b32 s68, v179, s18
	s_cselect_b32 s85, s74, s52
	s_cselect_b32 s86, s19, s75
	s_add_i32 s28, s91, 17
	s_add_i32 s29, s91, 18
	s_add_i32 s18, s91, 19
	v_readlane_b32 s84, v141, 0
	v_readlane_b32 s43, v141, 2
	v_readlane_b32 s42, v179, s15
	v_readlane_b32 s87, v140, s62
	global_load_dwordx4 v[70:73], v[0:1], off
	global_load_dwordx2 v[74:75], v[2:3], off offset:1024
	s_waitcnt vmcnt(15)
	s_and_b64 s[62:63], vcc, exec
	s_waitcnt vmcnt(14)
	v_cvt_scalef32_pk32_f32_fp6 v[0:31], v[52:57], 1.0
	v_pk_fma_f32 v[52:53], s[42:43], v[0:1], v[172:173] op_sel_hi:[0,1,1]
	v_pk_fma_f32 v[54:55], s[42:43], v[2:3], v[174:175] op_sel_hi:[0,1,1]
	v_pk_fma_f32 v[56:57], s[42:43], v[4:5], v[170:171] op_sel_hi:[0,1,1]
	v_pk_fma_f32 v[142:143], s[42:43], v[6:7], v[168:169] op_sel_hi:[0,1,1]
	v_pk_fma_f32 v[166:167], s[42:43], v[8:9], v[166:167] op_sel_hi:[0,1,1]
	v_pk_fma_f32 v[164:165], s[42:43], v[10:11], v[164:165] op_sel_hi:[0,1,1]
	v_pk_fma_f32 v[162:163], s[42:43], v[12:13], v[162:163] op_sel_hi:[0,1,1]
	v_pk_fma_f32 v[160:161], s[42:43], v[14:15], v[160:161] op_sel_hi:[0,1,1]
	v_pk_fma_f32 v[158:159], s[42:43], v[16:17], v[158:159] op_sel_hi:[0,1,1]
	v_pk_fma_f32 v[156:157], s[42:43], v[18:19], v[156:157] op_sel_hi:[0,1,1]
	v_pk_fma_f32 v[154:155], s[42:43], v[20:21], v[154:155] op_sel_hi:[0,1,1]
	v_pk_fma_f32 v[152:153], s[42:43], v[22:23], v[152:153] op_sel_hi:[0,1,1]
	v_pk_fma_f32 v[150:151], s[42:43], v[24:25], v[150:151] op_sel_hi:[0,1,1]
	v_pk_fma_f32 v[148:149], s[42:43], v[26:27], v[148:149] op_sel_hi:[0,1,1]
	v_pk_fma_f32 v[146:147], s[42:43], v[28:29], v[146:147] op_sel_hi:[0,1,1]
	v_pk_fma_f32 v[144:145], s[42:43], v[30:31], v[144:145] op_sel_hi:[0,1,1]
	v_readlane_b32 s42, v140, s28
	s_cselect_b32 s28, s84, s87
	v_readlane_b32 s62, v140, s29
	s_mul_hi_i32 s29, s28, 0x600
	s_mulk_i32 s28, 0x600
	v_readlane_b32 s47, v141, 1
	v_readlane_b32 s46, v179, s46
	s_waitcnt vmcnt(13)
	s_add_u32 s28, s86, s28
	s_waitcnt vmcnt(12)
	v_cvt_scalef32_pk32_f32_fp6 v[0:31], v[40:45], 1.0
	v_pk_fma_f32 v[40:41], s[46:47], v[0:1], v[52:53] op_sel_hi:[0,1,1]
	v_pk_fma_f32 v[42:43], s[46:47], v[2:3], v[54:55] op_sel_hi:[0,1,1]
	v_pk_fma_f32 v[44:45], s[46:47], v[4:5], v[56:57] op_sel_hi:[0,1,1]
	v_pk_fma_f32 v[52:53], s[46:47], v[6:7], v[142:143] op_sel_hi:[0,1,1]
	v_pk_fma_f32 v[54:55], s[46:47], v[8:9], v[166:167] op_sel_hi:[0,1,1]
	v_pk_fma_f32 v[56:57], s[46:47], v[10:11], v[164:165] op_sel_hi:[0,1,1]
	v_pk_fma_f32 v[142:143], s[46:47], v[12:13], v[162:163] op_sel_hi:[0,1,1]
	v_pk_fma_f32 v[160:161], s[46:47], v[14:15], v[160:161] op_sel_hi:[0,1,1]
	v_pk_fma_f32 v[158:159], s[46:47], v[16:17], v[158:159] op_sel_hi:[0,1,1]
	v_pk_fma_f32 v[156:157], s[46:47], v[18:19], v[156:157] op_sel_hi:[0,1,1]
	v_pk_fma_f32 v[154:155], s[46:47], v[20:21], v[154:155] op_sel_hi:[0,1,1]
	v_pk_fma_f32 v[152:153], s[46:47], v[22:23], v[152:153] op_sel_hi:[0,1,1]
	v_pk_fma_f32 v[150:151], s[46:47], v[24:25], v[150:151] op_sel_hi:[0,1,1]
	v_pk_fma_f32 v[148:149], s[46:47], v[26:27], v[148:149] op_sel_hi:[0,1,1]
	v_pk_fma_f32 v[146:147], s[46:47], v[28:29], v[146:147] op_sel_hi:[0,1,1]
	v_pk_fma_f32 v[144:145], s[46:47], v[30:31], v[144:145] op_sel_hi:[0,1,1]
	s_waitcnt vmcnt(11)
	s_addc_u32 s29, s85, s29
	s_waitcnt vmcnt(10)
	v_cvt_scalef32_pk32_f32_fp6 v[0:31], v[34:39], 1.0
	v_pk_fma_f32 v[34:35], s[68:69], v[0:1], v[40:41] op_sel_hi:[0,1,1]
	v_lshl_add_u64 v[0:1], s[28:29], 0, v[84:85]
	v_lshl_add_u64 v[36:37], s[28:29], 0, v[86:87]
	s_and_b64 s[28:29], vcc, exec
	s_cselect_b32 s28, s47, s42
	s_mul_hi_i32 s29, s28, 0x600
	s_mulk_i32 s28, 0x600
	s_add_u32 s28, s86, s28
	v_readlane_b32 s14, v179, s14
	v_pk_fma_f32 v[38:39], s[68:69], v[2:3], v[42:43] op_sel_hi:[0,1,1]
	v_pk_fma_f32 v[40:41], s[68:69], v[4:5], v[44:45] op_sel_hi:[0,1,1]
	v_pk_fma_f32 v[42:43], s[68:69], v[6:7], v[52:53] op_sel_hi:[0,1,1]
	v_pk_fma_f32 v[44:45], s[68:69], v[8:9], v[54:55] op_sel_hi:[0,1,1]
	v_pk_fma_f32 v[162:163], s[68:69], v[10:11], v[56:57] op_sel_hi:[0,1,1]
	v_pk_fma_f32 v[142:143], s[68:69], v[12:13], v[142:143] op_sel_hi:[0,1,1]
	v_pk_fma_f32 v[160:161], s[68:69], v[14:15], v[160:161] op_sel_hi:[0,1,1]
	v_pk_fma_f32 v[158:159], s[68:69], v[16:17], v[158:159] op_sel_hi:[0,1,1]
	v_pk_fma_f32 v[156:157], s[68:69], v[18:19], v[156:157] op_sel_hi:[0,1,1]
	v_pk_fma_f32 v[154:155], s[68:69], v[20:21], v[154:155] op_sel_hi:[0,1,1]
	v_pk_fma_f32 v[152:153], s[68:69], v[22:23], v[152:153] op_sel_hi:[0,1,1]
	v_pk_fma_f32 v[150:151], s[68:69], v[24:25], v[150:151] op_sel_hi:[0,1,1]
	v_pk_fma_f32 v[148:149], s[68:69], v[26:27], v[148:149] op_sel_hi:[0,1,1]
	v_pk_fma_f32 v[146:147], s[68:69], v[28:29], v[146:147] op_sel_hi:[0,1,1]
	v_pk_fma_f32 v[144:145], s[68:69], v[30:31], v[144:145] op_sel_hi:[0,1,1]
	s_waitcnt vmcnt(9)
; __device__ __forceinline__ float rl_f(float v, int l) { return __uint_as_float(__builtin_amdgcn_readlane(__float_as_uint(v), l)); }
; __device__ __forceinline__ void wr_lane(float& dst, float val_uniform, int lane_uniform, int lane) { asm volatile("" : "+s"(lane_uniform)); dst = (lane == lane_uniform) ? val_uniform : dst; }
; __device__ __forceinline__ void fma_row6(float (&out)[32], const Row6& R, float w) {
;     const v32f f = dq_row6(R, out[0]);
; #pragma unroll
;     for (int i = 0; i < 32; ++i) out[i] = fmaf(w, f[i], out[i]);
; __device__ __forceinline__ void peer_expert_tokens(const Ctx& F, CParams& P, int layer, int m_rows_all, bool last, bool dry, bool hide, unsigned* selflag, int k_lo, int k_hi) {
;     ...
;             for (int k = 0; k < 64; k += 8) {
; #pragma unroll
;                 for (int q = 0; q < 4; ++q) ld_row6(B[q], tabc, __builtin_amdgcn_readlane(idc, k + 4 + q), lane);
;                 if (seg < 2) { const float d0 = dot_row6(A[0], hf, chain), d1 = dot_row6(A[1], hf, chain), d2 = dot_row6(A[2], hf, chain), d3 = dot_row6(A[3], hf, chain); const float b = reduce4(d0, d1, d2, d3, lane);
; #pragma unroll
;                     for (int q = 0; q < 4; ++q) wr_lane(acc, rl_f(b, 16 * q), k + q, lane); }
;                 else {
; #pragma unroll
;                     for (int q = 0; q < 4; ++q) fma_row6(out, A[q], rl_f(wr, k + q)); }
;                 { const bool nx = k + 8 >= 64;
; #pragma unroll
;                   for (int q = 0; q < 4; ++q) { const int ec = __builtin_amdgcn_readlane(idc, (k + 8 + q) & 63), en = __builtin_amdgcn_readlane(idn, q);
;                       ld_row6(A[q], nx ? tabn : tabc, nx ? en : ec, lane); } }
;                 if (seg < 2) { const float d0 = dot_row6(B[0], hf, chain), d1 = dot_row6(B[1], hf, chain), d2 = dot_row6(B[2], hf, chain), d3 = dot_row6(B[3], hf, chain); const float b = reduce4(d0, d1, d2, d3, lane);
; #pragma unroll
;                     for (int q = 0; q < 4; ++q) wr_lane(acc, rl_f(b, 16 * q), k + 4 + q, lane); }
;                 else {
; #pragma unroll
;                     for (int q = 0; q < 4; ++q) fma_row6(out, B[q], rl_f(wr, k + 4 + q)); }
	global_load_dwordx4 v[52:55], v[0:1], off
	global_load_dwordx2 v[56:57], v[36:37], off offset:1024
	s_waitcnt vmcnt(10)
	v_cvt_scalef32_pk32_f32_fp6 v[0:31], v[46:51], 1.0
	s_addc_u32 s29, s85, s29
	v_pk_fma_f32 v[164:165], s[14:15], v[0:1], v[34:35] op_sel_hi:[0,1,1]
	v_pk_fma_f32 v[166:167], s[14:15], v[2:3], v[38:39] op_sel_hi:[0,1,1]
	v_lshl_add_u64 v[0:1], s[28:29], 0, v[84:85]
	v_lshl_add_u64 v[2:3], s[28:29], 0, v[86:87]
	s_and_b64 s[28:29], vcc, exec
	s_cselect_b32 s28, s43, s62
	s_mul_hi_i32 s29, s28, 0x600
	s_mulk_i32 s28, 0x600
	s_add_u32 s28, s86, s28
	s_addc_u32 s29, s85, s29
	v_readlane_b32 s49, v141, 3
	v_readlane_b32 s18, v140, s18
	v_pk_fma_f32 v[168:169], s[14:15], v[4:5], v[40:41] op_sel_hi:[0,1,1]
	v_pk_fma_f32 v[170:171], s[14:15], v[6:7], v[42:43] op_sel_hi:[0,1,1]
	v_pk_fma_f32 v[172:173], s[14:15], v[8:9], v[44:45] op_sel_hi:[0,1,1]
	global_load_dwordx4 v[40:43], v[0:1], off
	global_load_dwordx2 v[44:45], v[2:3], off offset:1024
	v_lshl_add_u64 v[0:1], s[28:29], 0, v[84:85]
	v_lshl_add_u64 v[2:3], s[28:29], 0, v[86:87]
	s_and_b64 s[28:29], vcc, exec
	s_cselect_b32 s18, s49, s18
	s_mul_hi_i32 s29, s18, 0x600
	s_mulk_i32 s18, 0x600
	s_add_u32 s28, s86, s18
	s_addc_u32 s29, s85, s29
	global_load_dwordx4 v[34:37], v[0:1], off
	global_load_dwordx2 v[38:39], v[2:3], off offset:1024
	v_lshl_add_u64 v[0:1], s[28:29], 0, v[84:85]
	v_lshl_add_u64 v[2:3], s[28:29], 0, v[86:87]
	global_load_dwordx4 v[46:49], v[0:1], off
	global_load_dwordx2 v[50:51], v[2:3], off offset:1024
	v_pk_fma_f32 v[162:163], s[14:15], v[10:11], v[162:163] op_sel_hi:[0,1,1]
	v_pk_fma_f32 v[142:143], s[14:15], v[12:13], v[142:143] op_sel_hi:[0,1,1]
	v_pk_fma_f32 v[160:161], s[14:15], v[14:15], v[160:161] op_sel_hi:[0,1,1]
	v_pk_fma_f32 v[158:159], s[14:15], v[16:17], v[158:159] op_sel_hi:[0,1,1]
	v_pk_fma_f32 v[156:157], s[14:15], v[18:19], v[156:157] op_sel_hi:[0,1,1]
	v_pk_fma_f32 v[154:155], s[14:15], v[20:21], v[154:155] op_sel_hi:[0,1,1]
	v_pk_fma_f32 v[152:153], s[14:15], v[22:23], v[152:153] op_sel_hi:[0,1,1]
	v_pk_fma_f32 v[150:151], s[14:15], v[24:25], v[150:151] op_sel_hi:[0,1,1]
	v_pk_fma_f32 v[148:149], s[14:15], v[26:27], v[148:149] op_sel_hi:[0,1,1]
	v_pk_fma_f32 v[146:147], s[14:15], v[28:29], v[146:147] op_sel_hi:[0,1,1]
	v_pk_fma_f32 v[144:145], s[14:15], v[30:31], v[144:145] op_sel_hi:[0,1,1]
	s_waitcnt vmcnt(15)
	s_mov_b32 s91, s15
	s_waitcnt vmcnt(14)
	v_cvt_scalef32_pk32_f32_fp6 v[0:31], v[58:63], 1.0
	v_pk_fma_f32 v[58:59], s[56:57], v[0:1], v[164:165] op_sel_hi:[0,1,1]
	v_pk_fma_f32 v[60:61], s[56:57], v[2:3], v[166:167] op_sel_hi:[0,1,1]
	v_pk_fma_f32 v[62:63], s[56:57], v[4:5], v[168:169] op_sel_hi:[0,1,1]
	v_pk_fma_f32 v[164:165], s[56:57], v[6:7], v[170:171] op_sel_hi:[0,1,1]
	v_pk_fma_f32 v[166:167], s[56:57], v[8:9], v[172:173] op_sel_hi:[0,1,1]
	v_pk_fma_f32 v[162:163], s[56:57], v[10:11], v[162:163] op_sel_hi:[0,1,1]
	v_pk_fma_f32 v[142:143], s[56:57], v[12:13], v[142:143] op_sel_hi:[0,1,1]
	v_pk_fma_f32 v[160:161], s[56:57], v[14:15], v[160:161] op_sel_hi:[0,1,1]
	v_pk_fma_f32 v[158:159], s[56:57], v[16:17], v[158:159] op_sel_hi:[0,1,1]
	v_pk_fma_f32 v[156:157], s[56:57], v[18:19], v[156:157] op_sel_hi:[0,1,1]
	v_pk_fma_f32 v[154:155], s[56:57], v[20:21], v[154:155] op_sel_hi:[0,1,1]
	v_pk_fma_f32 v[152:153], s[56:57], v[22:23], v[152:153] op_sel_hi:[0,1,1]
	v_pk_fma_f32 v[150:151], s[56:57], v[24:25], v[150:151] op_sel_hi:[0,1,1]
	v_pk_fma_f32 v[148:149], s[56:57], v[26:27], v[148:149] op_sel_hi:[0,1,1]
	v_pk_fma_f32 v[146:147], s[56:57], v[28:29], v[146:147] op_sel_hi:[0,1,1]
	v_pk_fma_f32 v[144:145], s[56:57], v[30:31], v[144:145] op_sel_hi:[0,1,1]
	s_waitcnt vmcnt(13)
	s_cmp_lt_u32 s15, 56
	s_waitcnt vmcnt(12)
	v_cvt_scalef32_pk32_f32_fp6 v[0:31], v[64:69], 1.0
	v_pk_fma_f32 v[58:59], s[66:67], v[0:1], v[58:59] op_sel_hi:[0,1,1]
	v_pk_fma_f32 v[60:61], s[66:67], v[2:3], v[60:61] op_sel_hi:[0,1,1]
	v_pk_fma_f32 v[62:63], s[66:67], v[4:5], v[62:63] op_sel_hi:[0,1,1]
	v_pk_fma_f32 v[64:65], s[66:67], v[6:7], v[164:165] op_sel_hi:[0,1,1]
	v_pk_fma_f32 v[66:67], s[66:67], v[8:9], v[166:167] op_sel_hi:[0,1,1]
	v_pk_fma_f32 v[68:69], s[66:67], v[10:11], v[162:163] op_sel_hi:[0,1,1]
	v_pk_fma_f32 v[142:143], s[66:67], v[12:13], v[142:143] op_sel_hi:[0,1,1]
	v_pk_fma_f32 v[160:161], s[66:67], v[14:15], v[160:161] op_sel_hi:[0,1,1]
	v_pk_fma_f32 v[158:159], s[66:67], v[16:17], v[158:159] op_sel_hi:[0,1,1]
	v_pk_fma_f32 v[156:157], s[66:67], v[18:19], v[156:157] op_sel_hi:[0,1,1]
	v_pk_fma_f32 v[154:155], s[66:67], v[20:21], v[154:155] op_sel_hi:[0,1,1]
	v_pk_fma_f32 v[152:153], s[66:67], v[22:23], v[152:153] op_sel_hi:[0,1,1]
	v_pk_fma_f32 v[150:151], s[66:67], v[24:25], v[150:151] op_sel_hi:[0,1,1]
	v_pk_fma_f32 v[148:149], s[66:67], v[26:27], v[148:149] op_sel_hi:[0,1,1]
	v_pk_fma_f32 v[146:147], s[66:67], v[28:29], v[146:147] op_sel_hi:[0,1,1]
	v_pk_fma_f32 v[144:145], s[66:67], v[30:31], v[144:145] op_sel_hi:[0,1,1]
	s_waitcnt vmcnt(11)
	s_waitcnt vmcnt(10)
	v_cvt_scalef32_pk32_f32_fp6 v[0:31], v[76:81], 1.0
	v_pk_fma_f32 v[58:59], s[80:81], v[0:1], v[58:59] op_sel_hi:[0,1,1]
	v_pk_fma_f32 v[60:61], s[80:81], v[2:3], v[60:61] op_sel_hi:[0,1,1]
	v_pk_fma_f32 v[62:63], s[80:81], v[4:5], v[62:63] op_sel_hi:[0,1,1]
	v_pk_fma_f32 v[64:65], s[80:81], v[6:7], v[64:65] op_sel_hi:[0,1,1]
	v_pk_fma_f32 v[66:67], s[80:81], v[8:9], v[66:67] op_sel_hi:[0,1,1]
	v_pk_fma_f32 v[68:69], s[80:81], v[10:11], v[68:69] op_sel_hi:[0,1,1]
	v_pk_fma_f32 v[76:77], s[80:81], v[12:13], v[142:143] op_sel_hi:[0,1,1]
	v_pk_fma_f32 v[78:79], s[80:81], v[14:15], v[160:161] op_sel_hi:[0,1,1]
	v_pk_fma_f32 v[80:81], s[80:81], v[16:17], v[158:159] op_sel_hi:[0,1,1]
	v_pk_fma_f32 v[142:143], s[80:81], v[18:19], v[156:157] op_sel_hi:[0,1,1]
	v_pk_fma_f32 v[154:155], s[80:81], v[20:21], v[154:155] op_sel_hi:[0,1,1]
	v_pk_fma_f32 v[152:153], s[80:81], v[22:23], v[152:153] op_sel_hi:[0,1,1]
	v_pk_fma_f32 v[150:151], s[80:81], v[24:25], v[150:151] op_sel_hi:[0,1,1]
	v_pk_fma_f32 v[148:149], s[80:81], v[26:27], v[148:149] op_sel_hi:[0,1,1]
	v_pk_fma_f32 v[146:147], s[80:81], v[28:29], v[146:147] op_sel_hi:[0,1,1]
	v_pk_fma_f32 v[144:145], s[80:81], v[30:31], v[144:145] op_sel_hi:[0,1,1]
	s_waitcnt vmcnt(9)
; __device__ __forceinline__ float rl_f(float v, int l) { return __uint_as_float(__builtin_amdgcn_readlane(__float_as_uint(v), l)); }
; __device__ __forceinline__ void peer_expert_tokens(const Ctx& F, CParams& P, int layer, int m_rows_all, bool last, bool dry, bool hide, unsigned* selflag, int k_lo, int k_hi) {
;     ...
; #pragma unroll
;                     for (int q = 0; q < 4; ++q) fma_row6(out, B[q], rl_f(wr, k + 4 + q)); }
;     ...
;         const int vs = vsel_of_row(t);
;         const float* gate = mod + (size_t)vs * 12288 + 5 * DM;
;         float* xr = X + (size_t)t * DM; float* dst = dry ? (float*)(F.ws + WS_OF) + (size_t)t * DM : (last ? P.out + (size_t)t * DM : xr);
;         float ssq = 0.f;
;         const unsigned lo4 = (unsigned)lane * 4u;
;         { f32x4 xo[8], gg[8];
; #pragma unroll
;           for (int q = 0; q < 8; ++q) { const unsigned c = lo4 + q * 256; xo[q] = *(const f32x4*)(xr + c); gg[q] = *(const f32x4*)(gate + c); }
; #pragma unroll
;           for (int q = 0; q < 8; ++q) { const unsigned c = lo4 + q * 256;
;             f32x4 y; y[0] = xo[q][0] + gg[q][0] * out[q * 4 + 0]; y[1] = xo[q][1] + gg[q][1] * out[q * 4 + 1]; y[2] = xo[q][2] + gg[q][2] * out[q * 4 + 2]; y[3] = xo[q][3] + gg[q][3] * out[q * 4 + 3];
;             *(f32x4*)(dst + c) = y;
;             out[q * 4 + 0] = y[0]; out[q * 4 + 1] = y[1]; out[q * 4 + 2] = y[2]; out[q * 4 + 3] = y[3];
;             ssq += y[0] * y[0] + y[1] * y[1] + y[2] * y[2] + y[3] * y[3]; } }
	s_waitcnt vmcnt(8)
	v_cvt_scalef32_pk32_f32_fp6 v[0:31], v[70:75], 1.0
	v_pk_fma_f32 v[172:173], s[94:95], v[0:1], v[58:59] op_sel_hi:[0,1,1]
	v_pk_fma_f32 v[174:175], s[94:95], v[2:3], v[60:61] op_sel_hi:[0,1,1]
	v_pk_fma_f32 v[170:171], s[94:95], v[4:5], v[62:63] op_sel_hi:[0,1,1]
	v_pk_fma_f32 v[168:169], s[94:95], v[6:7], v[64:65] op_sel_hi:[0,1,1]
	v_pk_fma_f32 v[166:167], s[94:95], v[8:9], v[66:67] op_sel_hi:[0,1,1]
	v_pk_fma_f32 v[164:165], s[94:95], v[10:11], v[68:69] op_sel_hi:[0,1,1]
	v_pk_fma_f32 v[162:163], s[94:95], v[12:13], v[76:77] op_sel_hi:[0,1,1]
	v_pk_fma_f32 v[160:161], s[94:95], v[14:15], v[78:79] op_sel_hi:[0,1,1]
	v_pk_fma_f32 v[158:159], s[94:95], v[16:17], v[80:81] op_sel_hi:[0,1,1]
	v_pk_fma_f32 v[156:157], s[94:95], v[18:19], v[142:143] op_sel_hi:[0,1,1]
	v_pk_fma_f32 v[154:155], s[94:95], v[20:21], v[154:155] op_sel_hi:[0,1,1]
	v_pk_fma_f32 v[152:153], s[94:95], v[22:23], v[152:153] op_sel_hi:[0,1,1]
	v_pk_fma_f32 v[150:151], s[94:95], v[24:25], v[150:151] op_sel_hi:[0,1,1]
	v_pk_fma_f32 v[148:149], s[94:95], v[26:27], v[148:149] op_sel_hi:[0,1,1]
	v_pk_fma_f32 v[146:147], s[94:95], v[28:29], v[146:147] op_sel_hi:[0,1,1]
	v_pk_fma_f32 v[144:145], s[94:95], v[30:31], v[144:145] op_sel_hi:[0,1,1]
	s_cbranch_scc1 .LBB0_2897
	s_cmpk_lt_u32 s48, 0x4000
	s_cselect_b32 s14, s95, 0x6000
	s_cmpk_gt_i32 s48, 0x1fff
	s_cselect_b32 s14, s14, 0
	s_lshl_b32 s14, s14, 2
	s_add_u32 s15, s53, s14
	s_addc_u32 s18, s26, 0
	s_add_u32 s28, s15, 0xa000
	s_addc_u32 s29, s18, 0
	s_ashr_i32 s49, s48, 31
	s_lshl_b64 s[42:43], s[48:49], 13
	s_add_u32 s46, s20, s42
	s_addc_u32 s47, s21, s43
	v_lshlrev_b64 v[66:67], 2, v[110:111]
	v_lshl_add_u64 v[24:25], s[46:47], 0, v[66:67]
	v_lshlrev_b64 v[72:73], 2, v[32:33]
	global_load_dwordx4 v[74:77], v[24:25], off nt
	v_lshl_add_u64 v[24:25], s[28:29], 0, v[66:67]
	v_lshlrev_b64 v[58:59], 2, v[112:113]
	v_lshl_add_u64 v[0:1], s[46:47], 0, v[72:73]
	v_lshl_add_u64 v[4:5], s[28:29], 0, v[72:73]
	v_lshlrev_b64 v[70:71], 2, v[106:107]
	global_load_dwordx4 v[78:81], v[24:25], off
	v_lshl_add_u64 v[24:25], s[46:47], 0, v[58:59]
	global_load_dwordx4 v[0:3], v[0:1], off nt
	v_lshl_add_u64 v[8:9], s[46:47], 0, v[70:71]
	global_load_dwordx4 v[4:7], v[4:5], off
	v_lshl_add_u64 v[12:13], s[28:29], 0, v[70:71]
	v_lshlrev_b64 v[68:69], 2, v[108:109]
	global_load_dwordx4 v[180:183], v[24:25], off nt
	v_lshl_add_u64 v[24:25], s[28:29], 0, v[58:59]
	v_lshlrev_b64 v[60:61], 2, v[114:115]
	global_load_dwordx4 v[8:11], v[8:9], off nt
	v_lshl_add_u64 v[16:17], s[46:47], 0, v[68:69]
	global_load_dwordx4 v[12:15], v[12:13], off
	v_lshl_add_u64 v[20:21], s[28:29], 0, v[68:69]
	global_load_dwordx4 v[184:187], v[24:25], off
	v_lshl_add_u64 v[24:25], s[46:47], 0, v[60:61]
	global_load_dwordx4 v[16:19], v[16:17], off nt
	v_lshlrev_b64 v[62:63], 2, v[116:117]
	global_load_dwordx4 v[20:23], v[20:21], off
	v_lshlrev_b64 v[64:65], 2, v[118:119]
	global_load_dwordx4 v[188:191], v[24:25], off nt
	v_lshl_add_u64 v[24:25], s[28:29], 0, v[60:61]
	global_load_dwordx4 v[192:195], v[24:25], off
	v_lshl_add_u64 v[24:25], s[46:47], 0, v[62:63]
	global_load_dwordx4 v[196:199], v[24:25], off nt
	v_lshl_add_u64 v[24:25], s[28:29], 0, v[62:63]
	global_load_dwordx4 v[200:203], v[24:25], off
	v_lshl_add_u64 v[24:25], s[46:47], 0, v[64:65]
	global_load_dwordx4 v[204:207], v[24:25], off nt
	v_lshl_add_u64 v[24:25], s[28:29], 0, v[64:65]
	global_load_dwordx4 v[216:219], v[24:25], off
	s_add_u32 s28, s16, s42
	s_addc_u32 s29, s31, s43
	s_andn2_b64 vcc, exec, s[92:93]
	s_waitcnt vmcnt(12)
	v_pk_fma_f32 v[28:29], v[172:173], v[4:5], v[0:1]
	v_pk_fma_f32 v[30:31], v[174:175], v[6:7], v[2:3]
	v_lshl_add_u64 v[0:1], s[28:29], 0, v[72:73]
	global_store_dwordx4 v[0:1], v[28:31], off nt
	v_lshl_add_u64 v[0:1], s[28:29], 0, v[70:71]
	s_waitcnt vmcnt(10)
	v_pk_fma_f32 v[24:25], v[170:171], v[12:13], v[8:9]
	v_pk_fma_f32 v[26:27], v[168:169], v[14:15], v[10:11]
	global_store_dwordx4 v[0:1], v[24:27], off nt
	v_lshl_add_u64 v[0:1], s[28:29], 0, v[68:69]
	s_waitcnt vmcnt(10)
	v_pk_fma_f32 v[12:13], v[158:159], v[184:185], v[180:181]
	v_pk_fma_f32 v[14:15], v[156:157], v[186:187], v[182:183]
	s_waitcnt vmcnt(8)
	v_pk_fma_f32 v[20:21], v[166:167], v[20:21], v[16:17]
	v_pk_fma_f32 v[22:23], v[164:165], v[22:23], v[18:19]
	global_store_dwordx4 v[0:1], v[20:23], off nt
	v_pk_fma_f32 v[16:17], v[162:163], v[78:79], v[74:75]
	v_pk_fma_f32 v[18:19], v[160:161], v[80:81], v[76:77]
	v_lshl_add_u64 v[0:1], s[28:29], 0, v[66:67]
	global_store_dwordx4 v[0:1], v[16:19], off nt
	v_lshl_add_u64 v[0:1], s[28:29], 0, v[58:59]
	global_store_dwordx4 v[0:1], v[12:15], off nt
	s_waitcnt vmcnt(9)
	v_pk_fma_f32 v[8:9], v[154:155], v[192:193], v[188:189]
	v_pk_fma_f32 v[10:11], v[152:153], v[194:195], v[190:191]
	v_lshl_add_u64 v[0:1], s[28:29], 0, v[60:61]
	global_store_dwordx4 v[0:1], v[8:11], off nt
	s_waitcnt vmcnt(8)
	v_pk_fma_f32 v[4:5], v[150:151], v[200:201], v[196:197]
	v_pk_fma_f32 v[6:7], v[148:149], v[202:203], v[198:199]
	v_lshl_add_u64 v[0:1], s[28:29], 0, v[62:63]
	global_store_dwordx4 v[0:1], v[4:7], off nt
	s_waitcnt vmcnt(7)
	v_pk_fma_f32 v[0:1], v[146:147], v[216:217], v[204:205]
	v_pk_fma_f32 v[2:3], v[144:145], v[218:219], v[206:207]
	v_lshl_add_u64 v[74:75], s[28:29], 0, v[64:65]
	global_store_dwordx4 v[74:75], v[0:3], off nt
	s_cbranch_vccnz .LBB0_2873
; __device__ __forceinline__ unsigned cvt_pk_bf16(float lo, float hi) { unsigned r; asm("v_cvt_pk_bf16_f32 %0, %1, %2" : "=v"(r) : "v"(lo), "v"(hi)); return r; }
; __device__ __forceinline__ void peer_expert_tokens(const Ctx& F, CParams& P, int layer, int m_rows_all, bool last, bool dry, bool hide, unsigned* selflag, int k_lo, int k_hi) {
;     ...
;             ssq += y[0] * y[0] + y[1] * y[1] + y[2] * y[2] + y[3] * y[3]; } }
;         if (!last && !dry) {
;             const float rstd = rsqrtf(wave_sum(ssq) * (1.f / DM) + EPS);
;             const float* gn = P.g_norm1 + (size_t)(layer + 1) * DM;
;             const float* shf = mod + (size_t)3 * 12288 + (size_t)vs * 12288; const float* scl = shf + DM;
;             bf16_t* hrow = (bf16_t*)(F.ws + WS_H) + (size_t)t * DM;
; #pragma unroll
;             for (int jh = 0; jh < 2; ++jh) { f32x4 g8[4], sc8[4], sh8[4];
; #pragma unroll
;                 for (int i = 0; i < 4; ++i) { const unsigned c = lo4 + (jh * 4 + i) * 256; g8[i] = *(const f32x4*)(gn + c); sc8[i] = *(const f32x4*)(scl + c); sh8[i] = *(const f32x4*)(shf + c); }
; #pragma unroll
;                 for (int i = 0; i < 4; ++i) { const int qg = jh * 4 + i; const f32x4 g = g8[i], sc = sc8[i], sh = sh8[i];
;                     float y[4];
; #pragma unroll
;                     for (int e2 = 0; e2 < 4; ++e2) y[e2] = (out[qg * 4 + e2] * rstd * g[e2]) * (1.f + sc[e2]) + sh[e2];
;                     u32x2 w; w.x = cvt_pk_bf16(y[0], y[1]); w.y = cvt_pk_bf16(y[2], y[3]);
;                     *(u32x2*)(hrow + lo4 + qg * 256) = w; } }
	v_pk_mul_f32 v[76:77], v[28:29], v[28:29]
	v_pk_mul_f32 v[74:75], v[30:31], v[30:31]
	v_pk_mul_f32 v[80:81], v[24:25], v[24:25]
	v_add_f32_e32 v76, v76, v77
	v_pk_mul_f32 v[78:79], v[26:27], v[26:27]
	v_pk_mul_f32 v[144:145], v[20:21], v[20:21]
	v_add_f32_e32 v80, v80, v81
	v_add_f32_e32 v74, v74, v76
	v_pk_mul_f32 v[142:143], v[22:23], v[22:23]
	v_add_f32_e32 v78, v78, v80
	v_add_f32_e32 v74, v75, v74
	v_add_f32_e32 v75, v144, v145
	v_add_f32_e32 v78, v79, v78
	v_add_f32_e32 v75, v142, v75
	v_pk_mul_f32 v[148:149], v[16:17], v[16:17]
	v_add_f32_e32 v74, v74, v78
	v_add_f32_e32 v75, v143, v75
	v_pk_mul_f32 v[146:147], v[18:19], v[18:19]
	v_add_f32_e32 v74, v74, v75
	v_add_f32_e32 v75, v148, v149
	s_lshl_b64 s[46:47], s[48:49], 11
	v_add_f32_e32 v75, v146, v75
	v_pk_mul_f32 v[152:153], v[12:13], v[12:13]
	v_add_f32_e32 v75, v147, v75
	s_add_u32 s14, s17, s14
	v_pk_mul_f32 v[150:151], v[14:15], v[14:15]
	v_add_f32_e32 v74, v74, v75
	v_add_f32_e32 v75, v152, v153
	s_addc_u32 s15, s24, 0
	v_add_f32_e32 v75, v150, v75
	s_add_u32 s42, s14, 0x2000
	v_pk_mul_f32 v[156:157], v[8:9], v[8:9]
	v_add_f32_e32 v75, v151, v75
	s_addc_u32 s43, s15, 0
	v_pk_mul_f32 v[154:155], v[10:11], v[10:11]
	v_add_f32_e32 v74, v74, v75
	v_add_f32_e32 v75, v156, v157
	v_lshl_add_u64 v[142:143], s[42:43], 0, v[72:73]
	v_add_f32_e32 v75, v154, v75
	global_load_dwordx4 v[78:81], v[120:121], off
	v_pk_mul_f32 v[160:161], v[4:5], v[4:5]
	global_load_dwordx4 v[142:145], v[142:143], off
	v_add_f32_e32 v75, v155, v75
	v_lshl_add_u64 v[72:73], s[14:15], 0, v[72:73]
	v_pk_mul_f32 v[158:159], v[6:7], v[6:7]
	v_add_f32_e32 v74, v74, v75
	v_add_f32_e32 v75, v160, v161
	global_load_dwordx4 v[146:149], v[72:73], off
	global_load_dwordx4 v[150:153], v[122:123], off
	v_add_f32_e32 v75, v158, v75
	v_lshl_add_u64 v[72:73], s[42:43], 0, v[70:71]
	v_pk_mul_f32 v[164:165], v[0:1], v[0:1]
	v_add_f32_e32 v75, v159, v75
	global_load_dwordx4 v[154:157], v[72:73], off
	v_pk_mul_f32 v[162:163], v[2:3], v[2:3]
	v_add_f32_e32 v74, v74, v75
	v_add_f32_e32 v75, v164, v165
	v_lshl_add_u64 v[70:71], s[14:15], 0, v[70:71]
	v_add_f32_e32 v75, v162, v75
	global_load_dwordx4 v[70:73], v[70:71], off
	s_nop 0
	global_load_dwordx4 v[158:161], v[124:125], off
	v_add_f32_e32 v75, v163, v75
	v_lshl_add_u64 v[162:163], s[42:43], 0, v[68:69]
	global_load_dwordx4 v[162:165], v[162:163], off
	v_lshl_add_u64 v[68:69], s[14:15], 0, v[68:69]
	global_load_dwordx4 v[166:169], v[68:69], off
	global_load_dwordx4 v[170:173], v[126:127], off
	v_lshl_add_u64 v[68:69], s[42:43], 0, v[66:67]
	global_load_dwordx4 v[180:183], v[68:69], off
	v_lshl_add_u64 v[66:67], s[14:15], 0, v[66:67]
	global_load_dwordx4 v[66:69], v[66:67], off
	v_add_f32_e32 v74, v74, v75
	ds_swizzle_b32 v75, v74 offset:swizzle(SWAP,16)
	s_waitcnt lgkmcnt(0)
	v_add_f32_e32 v74, v74, v75
	ds_swizzle_b32 v75, v74 offset:swizzle(SWAP,8)
	s_waitcnt lgkmcnt(0)
	v_add_f32_e32 v74, v74, v75
	ds_swizzle_b32 v75, v74 offset:swizzle(SWAP,4)
	s_waitcnt lgkmcnt(0)
	v_add_f32_e32 v74, v74, v75
	ds_swizzle_b32 v75, v74 offset:swizzle(SWAP,2)
	s_waitcnt lgkmcnt(0)
	v_add_f32_e32 v74, v74, v75
	ds_swizzle_b32 v75, v74 offset:swizzle(SWAP,1)
	s_waitcnt lgkmcnt(0)
	v_add_f32_e32 v74, v74, v75
	v_mov_b32_e32 v75, v74
	s_nop 1
	v_permlane32_swap_b32_e32 v74, v75
	v_add_f32_e32 v74, v74, v75
	v_fmamk_f32 v74, v74, 0x3a000000, v234
	v_cmp_gt_f32_e32 vcc, s57, v74
	v_mul_f32_e32 v75, 0x4b800000, v74
	s_waitcnt vmcnt(10)
	v_add_f32_e32 v77, 1.0, v142
	v_cndmask_b32_e32 v74, v74, v75, vcc
	v_rsq_f32_e32 v74, v74
	s_nop 0
	v_mul_f32_e32 v75, 0x45800000, v74
	v_cndmask_b32_e32 v76, v74, v75, vcc
	v_mul_f32_e32 v28, v28, v76
	v_mul_f32_e32 v28, v78, v28
	v_mul_f32_e32 v29, v29, v76
	s_waitcnt vmcnt(9)
	v_fma_f32 v28, v77, v28, v146
	v_mul_f32_e32 v29, v79, v29
	v_add_f32_e32 v77, 1.0, v143
	v_mul_f32_e32 v30, v30, v76
	v_fma_f32 v29, v77, v29, v147
	v_mul_f32_e32 v30, v80, v30
	v_add_f32_e32 v77, 1.0, v144
	v_mul_f32_e32 v31, v31, v76
	v_lshl_add_u64 v[74:75], s[46:47], 1, v[88:89]
	v_fma_f32 v30, v77, v30, v148
	v_mul_f32_e32 v31, v81, v31
	v_add_f32_e32 v77, 1.0, v145
	v_cvt_pk_bf16_f32 v28, v28, v29
	v_mul_f32_e32 v24, v24, v76
	v_fmac_f32_e32 v149, v77, v31
	v_cvt_pk_bf16_f32 v29, v30, v149
	global_store_dwordx2 v[74:75], v[28:29], off
	s_waitcnt vmcnt(9)
	v_mul_f32_e32 v24, v150, v24
	s_waitcnt vmcnt(8)
	v_add_f32_e32 v28, 1.0, v154
	v_mul_f32_e32 v25, v25, v76
	s_waitcnt vmcnt(7)
	v_fma_f32 v24, v28, v24, v70
	v_mul_f32_e32 v25, v151, v25
	v_add_f32_e32 v28, 1.0, v155
	v_mul_f32_e32 v26, v26, v76
	v_fma_f32 v25, v28, v25, v71
	v_mul_f32_e32 v26, v152, v26
	v_add_f32_e32 v28, 1.0, v156
	v_mul_f32_e32 v27, v27, v76
	v_fma_f32 v26, v28, v26, v72
	v_mul_f32_e32 v27, v153, v27
	v_add_f32_e32 v28, 1.0, v157
	v_cvt_pk_bf16_f32 v24, v24, v25
	v_mul_f32_e32 v20, v20, v76
	v_fmac_f32_e32 v73, v28, v27
	v_cvt_pk_bf16_f32 v25, v26, v73
	global_store_dwordx2 v[74:75], v[24:25], off offset:512
	s_waitcnt vmcnt(7)
; __device__ __forceinline__ unsigned cvt_pk_bf16(float lo, float hi) { unsigned r; asm("v_cvt_pk_bf16_f32 %0, %1, %2" : "=v"(r) : "v"(lo), "v"(hi)); return r; }
; __device__ __forceinline__ void peer_expert_tokens(const Ctx& F, CParams& P, int layer, int m_rows_all, bool last, bool dry, bool hide, unsigned* selflag, int k_lo, int k_hi) {
;     ...
;             for (int jh = 0; jh < 2; ++jh) { f32x4 g8[4], sc8[4], sh8[4];
; #pragma unroll
;                 for (int i = 0; i < 4; ++i) { const unsigned c = lo4 + (jh * 4 + i) * 256; g8[i] = *(const f32x4*)(gn + c); sc8[i] = *(const f32x4*)(scl + c); sh8[i] = *(const f32x4*)(shf + c); }
; #pragma unroll
;                 for (int i = 0; i < 4; ++i) { const int qg = jh * 4 + i; const f32x4 g = g8[i], sc = sc8[i], sh = sh8[i];
;                     float y[4];
; #pragma unroll
;                     for (int e2 = 0; e2 < 4; ++e2) y[e2] = (out[qg * 4 + e2] * rstd * g[e2]) * (1.f + sc[e2]) + sh[e2];
;                     u32x2 w; w.x = cvt_pk_bf16(y[0], y[1]); w.y = cvt_pk_bf16(y[2], y[3]);
;                     *(u32x2*)(hrow + lo4 + qg * 256) = w; } }
	v_mul_f32_e32 v20, v158, v20
	s_waitcnt vmcnt(6)
	v_add_f32_e32 v24, 1.0, v162
	v_mul_f32_e32 v21, v21, v76
	s_waitcnt vmcnt(5)
	v_fma_f32 v20, v24, v20, v166
	v_mul_f32_e32 v21, v159, v21
	v_add_f32_e32 v24, 1.0, v163
	v_mul_f32_e32 v22, v22, v76
	v_fma_f32 v21, v24, v21, v167
	v_mul_f32_e32 v22, v160, v22
	v_add_f32_e32 v24, 1.0, v164
	v_mul_f32_e32 v23, v23, v76
	v_fma_f32 v22, v24, v22, v168
	v_mul_f32_e32 v23, v161, v23
	v_add_f32_e32 v24, 1.0, v165
	v_cvt_pk_bf16_f32 v20, v20, v21
	v_mul_f32_e32 v16, v16, v76
	v_fmac_f32_e32 v169, v24, v23
	v_cvt_pk_bf16_f32 v21, v22, v169
	global_store_dwordx2 v[74:75], v[20:21], off offset:1024
	s_waitcnt vmcnt(5)
	v_mul_f32_e32 v16, v16, v170
	s_waitcnt vmcnt(4)
	v_add_f32_e32 v20, 1.0, v180
	v_mul_f32_e32 v17, v17, v76
	s_waitcnt vmcnt(3)
	v_fma_f32 v16, v16, v20, v66
	v_mul_f32_e32 v17, v17, v171
	v_add_f32_e32 v20, 1.0, v181
	v_mul_f32_e32 v18, v18, v76
	v_fma_f32 v17, v17, v20, v67
	v_mul_f32_e32 v18, v18, v172
	v_add_f32_e32 v20, 1.0, v182
	v_mul_f32_e32 v19, v19, v76
	v_fma_f32 v18, v18, v20, v68
	v_mul_f32_e32 v19, v19, v173
	v_add_f32_e32 v20, 1.0, v183
	v_fmac_f32_e32 v69, v19, v20
	v_cvt_pk_bf16_f32 v16, v16, v17
	v_cvt_pk_bf16_f32 v17, v18, v69
	global_store_dwordx2 v[74:75], v[16:17], off offset:1536
	v_lshl_add_u64 v[20:21], s[42:43], 0, v[58:59]
	global_load_dwordx4 v[16:19], v[128:129], off
	v_lshl_add_u64 v[24:25], s[14:15], 0, v[58:59]
	global_load_dwordx4 v[20:23], v[20:21], off
	s_nop 0
	global_load_dwordx4 v[24:27], v[24:25], off
	s_nop 0
	global_load_dwordx4 v[28:31], v[130:131], off
	v_lshl_add_u64 v[58:59], s[42:43], 0, v[60:61]
	global_load_dwordx4 v[66:69], v[58:59], off
	v_lshl_add_u64 v[58:59], s[14:15], 0, v[60:61]
	global_load_dwordx4 v[58:61], v[58:59], off
	s_nop 0
	global_load_dwordx4 v[70:73], v[132:133], off
	v_lshl_add_u64 v[78:79], s[42:43], 0, v[62:63]
	global_load_dwordx4 v[78:81], v[78:79], off
	v_lshl_add_u64 v[62:63], s[14:15], 0, v[62:63]
	global_load_dwordx4 v[142:145], v[62:63], off
	global_load_dwordx4 v[146:149], v[134:135], off
	v_lshl_add_u64 v[62:63], s[42:43], 0, v[64:65]
	global_load_dwordx4 v[150:153], v[62:63], off
	v_lshl_add_u64 v[62:63], s[14:15], 0, v[64:65]
	global_load_dwordx4 v[62:65], v[62:63], off
	v_mul_f32_e32 v12, v12, v76
	v_mul_f32_e32 v13, v13, v76
	v_mul_f32_e32 v14, v14, v76
	v_mul_f32_e32 v15, v15, v76
	v_mul_f32_e32 v8, v8, v76
	v_mul_f32_e32 v9, v9, v76
	v_mul_f32_e32 v10, v10, v76
	v_mul_f32_e32 v11, v11, v76
	v_mul_f32_e32 v4, v4, v76
	v_mul_f32_e32 v5, v5, v76
	v_mul_f32_e32 v6, v6, v76
	v_mul_f32_e32 v7, v7, v76
	v_mul_f32_e32 v0, v0, v76
	v_mul_f32_e32 v1, v1, v76
	v_mul_f32_e32 v2, v2, v76
	v_mul_f32_e32 v3, v3, v76
	s_waitcnt vmcnt(11)
	v_mul_f32_e32 v12, v12, v16
	v_mul_f32_e32 v13, v13, v17
	s_waitcnt vmcnt(10)
	v_add_f32_e32 v16, 1.0, v20
	s_waitcnt vmcnt(9)
	v_fma_f32 v12, v12, v16, v24
	v_add_f32_e32 v16, 1.0, v21
	v_fma_f32 v13, v13, v16, v25
	v_mul_f32_e32 v14, v14, v18
	v_add_f32_e32 v16, 1.0, v22
	v_fma_f32 v14, v14, v16, v26
	v_mul_f32_e32 v15, v15, v19
	v_add_f32_e32 v16, 1.0, v23
	v_cvt_pk_bf16_f32 v12, v12, v13
	v_fmac_f32_e32 v27, v15, v16
	v_cvt_pk_bf16_f32 v13, v14, v27
	global_store_dwordx2 v[74:75], v[12:13], off offset:2048
	s_waitcnt vmcnt(9)
	v_mul_f32_e32 v8, v8, v28
	s_waitcnt vmcnt(8)
	v_add_f32_e32 v12, 1.0, v66
	s_waitcnt vmcnt(7)
	v_fma_f32 v8, v8, v12, v58
	v_mul_f32_e32 v9, v9, v29
	v_add_f32_e32 v12, 1.0, v67
	v_fma_f32 v9, v9, v12, v59
	v_mul_f32_e32 v10, v10, v30
	v_add_f32_e32 v12, 1.0, v68
	v_fma_f32 v10, v10, v12, v60
	v_mul_f32_e32 v11, v11, v31
	v_add_f32_e32 v12, 1.0, v69
	v_cvt_pk_bf16_f32 v8, v8, v9
	v_fmac_f32_e32 v61, v11, v12
	v_cvt_pk_bf16_f32 v9, v10, v61
	global_store_dwordx2 v[74:75], v[8:9], off offset:2560
	s_waitcnt vmcnt(7)
	v_mul_f32_e32 v4, v4, v70
	s_waitcnt vmcnt(6)
	v_add_f32_e32 v8, 1.0, v78
	s_waitcnt vmcnt(5)
	v_fma_f32 v4, v4, v8, v142
	v_mul_f32_e32 v5, v5, v71
	v_add_f32_e32 v8, 1.0, v79
	v_fma_f32 v5, v5, v8, v143
	v_mul_f32_e32 v6, v6, v72
	v_add_f32_e32 v8, 1.0, v80
	v_fma_f32 v6, v6, v8, v144
	v_mul_f32_e32 v7, v7, v73
	v_add_f32_e32 v8, 1.0, v81
	v_cvt_pk_bf16_f32 v4, v4, v5
	v_fmac_f32_e32 v145, v7, v8
	v_cvt_pk_bf16_f32 v5, v6, v145
	global_store_dwordx2 v[74:75], v[4:5], off offset:3072
	s_waitcnt vmcnt(5)
	v_mul_f32_e32 v0, v0, v146
	s_waitcnt vmcnt(4)
	v_add_f32_e32 v4, 1.0, v150
	s_waitcnt vmcnt(3)
	v_fma_f32 v0, v0, v4, v62
	v_mul_f32_e32 v1, v1, v147
	v_add_f32_e32 v4, 1.0, v151
	v_fma_f32 v1, v1, v4, v63
	v_mul_f32_e32 v2, v2, v148
	v_add_f32_e32 v4, 1.0, v152
	v_fma_f32 v2, v2, v4, v64
	v_mul_f32_e32 v3, v3, v149
	v_add_f32_e32 v4, 1.0, v153
	v_fmac_f32_e32 v65, v3, v4
	v_cvt_pk_bf16_f32 v0, v0, v1
	v_cvt_pk_bf16_f32 v1, v2, v65
	global_store_dwordx2 v[74:75], v[0:1], off offset:3584
	s_branch .LBB0_2873
